# ph8/ph13: workgroups 0..127 run their half tile first, full tile second (epilogue/main-loop overlap across chip halves)
# baseline (speedup 1.0000x reference)
.LBB0_681:
	s_mov_b32 s16, s39
	s_mov_b32 s100, 0
	s_cmp_gt_i32 s39, 0x7f
	s_cbranch_scc1 .Lh13_sw
	s_and_b32 s100, s39, 1
	s_add_i32 s100, s100, 1
	s_lshr_b32 s16, s39, 1
	s_addk_i32 s16, 0x100
.Lh13_sw:
	v_mov_b32_e32 v0, v179
	s_movk_i32 s56, 0x400
	v_readfirstlane_b32 s43, v0
	s_cmpk_gt_i32 s16, 0x13f
	s_cbranch_scc1 .LBB0_701
	v_lshlrev_b32_e32 v2, 4, v0
	v_add_u32_e32 v3, 0x2000, v2
	v_ashrrev_i32_e32 v4, 31, v3
	v_lshrrev_b32_e32 v4, 22, v4
	v_add_u32_e32 v4, v3, v4
	v_ashrrev_i32_e32 v4, 10, v4
	v_mul_i32_i24_e32 v6, 0x400, v4
	v_sub_u32_e32 v3, v3, v6
	v_lshrrev_b32_e32 v6, 4, v3
	v_bitop3_b32 v3, v6, v3, 32 bitop3:0x6c
	v_ashrrev_i32_e32 v6, 31, v3
	v_lshrrev_b32_e32 v6, 26, v6
	v_add_u32_e32 v6, v3, v6
	s_add_u32 s17, s46, 0xb400000
	v_ashrrev_i32_e32 v7, 6, v6
	v_and_b32_e32 v6, 0xc0, v6
	s_addc_u32 s21, s47, 0
	s_load_dwordx2 s[18:19], s[0:1], 0x50
	s_lshl_b32 s0, s8, 20
	v_sub_u32_e32 v3, v3, v6
	s_and_b32 s0, s0, 0x200000
	v_lshlrev_b32_e32 v5, 5, v4
	v_ashrrev_i16_sdwa v3, v230, sext(v3) dst_sel:DWORD dst_unused:UNUSED_PAD src0_sel:DWORD src1_sel:BYTE_0
	v_lshlrev_b32_e32 v4, 3, v4
	s_add_u32 s0, s46, s0
	v_and_b32_e32 v5, 32, v5
	v_bfe_i32 v3, v3, 0, 16
	v_and_b32_e32 v4, -16, v4
	s_addc_u32 s1, s47, 0
	v_add_u32_e32 v4, v7, v4
	v_add_lshl_u32 v3, v5, v3, 1
	v_bfe_i32 v5, v0, 27, 1
	s_add_u32 s22, s0, 0x5900000
	v_and_b32_e32 v6, 3, v7
	s_mov_b32 s0, 0x1fffe0
	v_lshrrev_b32_e32 v7, 2, v4
	v_lshlrev_b32_e32 v8, 1, v4
	v_lshrrev_b32_e32 v5, 22, v5
	v_and_or_b32 v6, v4, s0, v6
	v_and_b32_e32 v7, 4, v7
	v_and_b32_e32 v8, 24, v8
	v_add_u32_e32 v5, v2, v5
	v_or3_b32 v6, v6, v7, v8
	v_and_b32_e32 v5, 0xfffffc00, v5
	v_lshl_add_u32 v170, v6, 11, v3
	v_lshl_add_u32 v172, v4, 11, v3
	v_ashrrev_i32_e32 v3, 31, v0
	v_sub_u32_e32 v2, v2, v5
	v_lshrrev_b32_e32 v3, 26, v3
	v_lshrrev_b32_e32 v5, 4, v2
	v_add_u32_e32 v3, v0, v3
	v_bitop3_b32 v5, v5, v2, 32 bitop3:0x6c
	v_ashrrev_i32_e32 v2, 31, v2
	v_ashrrev_i32_e32 v3, 6, v3
	v_lshrrev_b32_e32 v2, 26, v2
	v_lshlrev_b32_e32 v4, 5, v3
	v_add_u32_e32 v2, v5, v2
	v_lshlrev_b32_e32 v3, 3, v3
	v_ashrrev_i32_e32 v2, 6, v2
	v_and_b32_e32 v3, -16, v3
	s_addc_u32 s23, s1, 0
	v_mul_i32_i24_e32 v6, 64, v2
	v_add_u32_e32 v3, v2, v3
	v_and_b32_e32 v2, 3, v2
	s_ashr_i32 s39, s16, 31
	v_and_or_b32 v2, v3, s0, v2
	s_lshr_b32 s0, s39, 29
	s_add_i32 s0, s16, s0
	s_ashr_i32 s34, s43, 6
	s_ashr_i32 s1, s0, 3
	s_and_b32 s0, s0, -8
	s_ashr_i32 s35, s43, 8
	s_lshl_b32 s25, s34, 10
	s_sub_i32 s0, s16, s0
	s_cmp_lt_i32 s0, 0
	s_cselect_b32 s2, 41, 40
	s_mul_i32 s0, s2, s0
	s_add_i32 s0, s0, s1
	s_ashr_i32 s1, s0, 31
	s_lshr_b32 s1, s1, 28
	s_add_i32 s1, s0, s1
	s_ashr_i32 s2, s1, 4
	s_and_b32 s1, s1, 0xfff0
	s_sub_i32 s0, s0, s1
	s_bfe_i32 s1, s0, 0x80000
	s_bfe_u32 s1, s1, 0x2000d
	s_add_i32 s1, s0, s1
	s_bfe_i32 s3, s1, 0x80000
	s_and_b32 s1, s1, 0xfc
	s_sub_i32 s0, s0, s1
	s_lshl_b32 s2, s2, 2
	s_sext_i32_i16 s3, s3
	s_sext_i32_i8 s0, s0
	s_lshr_b32 s42, s3, 2
	s_add_i32 s0, s2, s0
	v_sub_u32_e32 v5, v5, v6
	s_ashr_i32 s1, s0, 31
	s_bfe_i64 s[2:3], s[42:43], 0x100000
	v_ashrrev_i16_sdwa v5, v230, sext(v5) dst_sel:DWORD dst_unused:UNUSED_PAD src0_sel:DWORD src1_sel:BYTE_0
	v_lshrrev_b32_e32 v6, 2, v3
	v_lshlrev_b32_e32 v7, 1, v3
	s_lshl_b64 s[26:27], s[0:1], 19
	s_lshl_b64 s[2:3], s[2:3], 19
	v_and_b32_e32 v4, 32, v4
	v_bfe_i32 v5, v5, 0, 16
	v_and_b32_e32 v6, 4, v6
	v_and_b32_e32 v7, 24, v7
	s_add_u32 s2, s22, s2
	v_or3_b32 v2, v2, v6, v7
	v_add_lshl_u32 v4, v4, v5, 1
	s_addc_u32 s3, s23, s3
	s_add_i32 s67, s25, 0
	v_lshl_add_u32 v194, v2, 11, v4
	s_mov_b64 s[30:31], s[2:3]
	s_add_i32 m0, s67, 0x10000
	v_lshl_add_u32 v196, v3, 11, v4
	global_load_lds_dwordx4 v194, s[30:31]
	s_add_i32 m0, s67, 0x12000
	s_add_u32 s54, s2, 0x40000
	s_addc_u32 s55, s3, 0
	global_load_lds_dwordx4 v170, s[30:31]
	s_mov_b64 s[30:31], s[54:55]
	s_add_i32 m0, s67, 0x14000
	s_nop 0
	global_load_lds_dwordx4 v194, s[30:31]
	s_add_i32 m0, s67, 0x16000
	s_add_u32 s26, s17, s26
	s_addc_u32 s27, s21, s27
	s_cmp_lg_u32 s100, 2
	s_cbranch_scc1 .Lh13_sx
	s_add_u32 s26, s26, 0x40000
	s_addc_u32 s27, s27, 0
.Lh13_sx:
	global_load_lds_dwordx4 v170, s[30:31]
	s_mov_b64 s[30:31], s[26:27]
	s_mov_b32 m0, s67
	s_add_i32 s68, s67, 0x2000
	s_nop 0
	global_load_lds_dwordx4 v196, s[30:31]
	s_mov_b32 m0, s68
	s_nop 0
	global_load_lds_dwordx4 v172, s[30:31]
	s_add_u32 s30, s26, 0x40000
	s_addc_u32 s31, s27, 0
	s_add_i32 s69, s67, 0x4000
	s_mov_b32 m0, s69
	s_add_i32 s70, s67, 0x6000
	s_cmp_eq_u32 s35, 1
	global_load_lds_dwordx4 v196, s[30:31]
	s_mov_b32 m0, s70
	s_cselect_b64 s[50:51], -1, 0
	global_load_lds_dwordx4 v172, s[30:31]
	s_cmp_lg_u32 s35, 1
	s_cbranch_scc1 .LBB0_684
	s_barrier
.LBB0_684:
	v_readlane_b32 s30, v255, 31
	v_readlane_b32 s31, v255, 32
	s_mov_b32 s61, s31
	s_mul_i32 s60, s8, 0xd800
	s_lshl_b64 s[30:31], s[60:61], 2
	s_add_u32 s1, s46, s30
	s_addc_u32 s40, s47, s31
	s_add_u32 s71, s46, 0x5e00000
	s_addc_u32 s78, s47, 0
	s_add_u32 s79, s1, 0x2000
	s_mov_b32 s31, s61
	s_addc_u32 s80, s40, 0
	s_lshl_b32 s60, s8, 10
	v_writelane_b32 v255, s30, 31
	v_mov_b32_e32 v195, v1
	s_waitcnt vmcnt(2)
	s_barrier
	v_writelane_b32 v255, s31, 32
	s_lshl_b64 s[30:31], s[60:61], 2
	s_waitcnt lgkmcnt(0)
	s_add_u32 s30, s18, s30
	s_addc_u32 s31, s19, s31
	s_add_u32 s81, s1, 0x4000
	s_addc_u32 s40, s40, 0
	s_ashr_i32 s1, s56, 31
	s_lshr_b32 s1, s1, 26
	s_add_i32 s1, s56, s1
	s_lshl_b32 s18, s34, 12
	s_ashr_i32 s41, s1, 6
	s_lshl_b32 s1, s35, 13
	s_and_b32 s57, s18, 0x3000
	s_add_u32 s34, s46, 0x6000000
	s_addc_u32 s35, s47, 0
	s_add_u32 s18, s2, 0x80
	s_addc_u32 s19, s3, 0
	s_add_i32 m0, s67, 0x18000
	v_lshl_add_u64 v[2:3], s[18:19], 0, v[194:195]
	v_mov_b32_e32 v171, v1
	global_load_lds_dwordx4 v[2:3], off
	s_add_i32 m0, s67, 0x1a000
	v_lshl_add_u64 v[2:3], s[18:19], 0, v[170:171]
	s_add_u32 s18, s26, 0x80
	v_mov_b32_e32 v197, v1
	s_addc_u32 s19, s27, 0
	s_add_i32 s82, s67, 0x8000
	v_mov_b32_e32 v173, v1
	global_load_lds_dwordx4 v[2:3], off
	s_mov_b32 m0, s82
	v_lshl_add_u64 v[2:3], s[18:19], 0, v[196:197]
	s_add_i32 s83, s67, 0xa000
	global_load_lds_dwordx4 v[2:3], off
	v_lshl_add_u64 v[2:3], s[18:19], 0, v[172:173]
	s_add_u32 s18, s54, 0x80
	s_mov_b32 m0, s83
	s_addc_u32 s19, s55, 0
	global_load_lds_dwordx4 v[2:3], off
	s_add_i32 m0, s67, 0x1c000
	v_lshl_add_u64 v[2:3], s[18:19], 0, v[194:195]
	global_load_lds_dwordx4 v[2:3], off
	v_lshl_add_u64 v[2:3], s[18:19], 0, v[170:171]
	s_add_i32 m0, s67, 0x1e000
	s_cmp_gt_i32 s56, 63
	global_load_lds_dwordx4 v[2:3], off
	v_and_b32_e32 v2, 15, v0
	v_and_b32_e32 v3, 48, v0
	v_lshlrev_b32_e32 v2, 6, v2
	v_lshlrev_b32_e32 v0, 2, v0
	s_cselect_b64 s[46:47], -1, 0
	s_add_i32 s84, s41, -2
	v_or_b32_e32 v4, v2, v3
	v_and_b32_e32 v0, 32, v0
	s_waitcnt vmcnt(6)
	s_cmpk_lt_u32 s43, 0x100
	v_bitop3_b32 v2, v2, v0, v3 bitop3:0x36
	v_bitop3_b32 v0, v4, s1, v0 bitop3:0xde
	s_cselect_b64 s[54:55], -1, 0
	s_add_u32 s85, s36, 0xff000000
	s_sext_i32_i8 s88, s42
	v_or_b32_e32 v222, s57, v2
	s_addc_u32 s86, s37, -1
	s_mov_b32 s87, 0
	s_mov_b32 s101, 0
	v_add_u32_e32 v223, 0, v0
	s_barrier
	s_branch .LBB0_687

.LBB0_687:
	s_add_i32 s87, s87, 1
	s_mul_i32 s1, s87, s15
	s_mul_hi_u32 s18, s87, s64
	s_add_i32 s1, s18, s1
	s_mul_i32 s18, s87, s64
	s_add_u32 s18, s18, s16
	s_addc_u32 s19, s1, s39
	s_mov_b32 s101, 0
	s_cmp_lg_u32 s87, 1
	s_cbranch_scc1 .Lh13_a
	s_movk_i32 s18, 0x140
	s_mov_b32 s19, 0
	v_readlane_b32 s101, v254, 8
	s_cmp_gt_i32 s101, 0x7f
	s_cbranch_scc1 .Lh13_a0
	s_mov_b32 s18, s101
.Lh13_a0:
	s_mov_b32 s101, 0

.Lh8_sw:
	v_mov_b32_e32 v0, v179
	s_movk_i32 s54, 0x400
	v_readfirstlane_b32 s41, v0
	s_cmpk_gt_i32 s16, 0x13f
	s_cbranch_scc1 .LBB0_1325
	v_lshlrev_b32_e32 v2, 4, v0
	v_add_u32_e32 v3, 0x2000, v2
	v_ashrrev_i32_e32 v4, 31, v3
	v_lshrrev_b32_e32 v4, 22, v4
	v_add_u32_e32 v4, v3, v4
	v_ashrrev_i32_e32 v4, 10, v4
	v_mul_i32_i24_e32 v6, 0x400, v4
	v_sub_u32_e32 v3, v3, v6
	v_lshrrev_b32_e32 v6, 4, v3
	v_bitop3_b32 v3, v6, v3, 32 bitop3:0x6c
	v_ashrrev_i32_e32 v6, 31, v3
	v_lshrrev_b32_e32 v6, 26, v6
	v_add_u32_e32 v6, v3, v6
	v_ashrrev_i32_e32 v7, 6, v6
	v_and_b32_e32 v6, 0xc0, v6
	s_add_u32 s17, s46, 0x8800000
	v_sub_u32_e32 v3, v3, v6
	s_addc_u32 s21, s47, 0
	s_load_dwordx2 s[18:19], s[0:1], 0x50
	s_lshl_b32 s0, s8, 20
	v_lshlrev_b32_e32 v5, 5, v4
	v_ashrrev_i16_sdwa v3, v230, sext(v3) dst_sel:DWORD dst_unused:UNUSED_PAD src0_sel:DWORD src1_sel:BYTE_0
	v_lshlrev_b32_e32 v4, 3, v4
	s_add_u32 s0, s46, s0
	v_and_b32_e32 v5, 32, v5
	v_bfe_i32 v3, v3, 0, 16
	v_and_b32_e32 v4, -16, v4
	s_addc_u32 s1, s47, 0
	v_add_u32_e32 v4, v7, v4
	v_add_lshl_u32 v3, v5, v3, 1
	v_bfe_i32 v5, v0, 27, 1
	s_add_u32 s22, s0, 0x4c00000
	v_and_b32_e32 v6, 3, v7
	s_mov_b32 s0, 0x1fffe0
	v_lshrrev_b32_e32 v7, 2, v4
	v_lshlrev_b32_e32 v8, 1, v4
	v_lshrrev_b32_e32 v5, 22, v5
	v_and_or_b32 v6, v4, s0, v6
	v_and_b32_e32 v7, 4, v7
	v_and_b32_e32 v8, 24, v8
	v_add_u32_e32 v5, v2, v5
	v_or3_b32 v6, v6, v7, v8
	v_and_b32_e32 v5, 0xfffffc00, v5
	v_lshl_add_u32 v170, v6, 11, v3
	v_lshl_add_u32 v172, v4, 11, v3
	v_ashrrev_i32_e32 v3, 31, v0
	v_sub_u32_e32 v2, v2, v5
	v_lshrrev_b32_e32 v3, 26, v3
	v_lshrrev_b32_e32 v5, 4, v2
	v_add_u32_e32 v3, v0, v3
	v_bitop3_b32 v5, v5, v2, 32 bitop3:0x6c
	v_ashrrev_i32_e32 v2, 31, v2
	v_ashrrev_i32_e32 v3, 6, v3
	v_lshrrev_b32_e32 v2, 26, v2
	v_lshlrev_b32_e32 v4, 5, v3
	v_add_u32_e32 v2, v5, v2
	v_lshlrev_b32_e32 v3, 3, v3
	v_ashrrev_i32_e32 v2, 6, v2
	v_and_b32_e32 v3, -16, v3
	s_addc_u32 s23, s1, 0
	v_mul_i32_i24_e32 v6, 64, v2
	v_add_u32_e32 v3, v2, v3
	v_and_b32_e32 v2, 3, v2
	s_ashr_i32 s39, s16, 31
	v_and_or_b32 v2, v3, s0, v2
	s_lshr_b32 s0, s39, 29
	s_add_i32 s0, s16, s0
	s_ashr_i32 s34, s41, 6
	s_ashr_i32 s1, s0, 3
	s_and_b32 s0, s0, -8
	s_ashr_i32 s35, s41, 8
	s_lshl_b32 s25, s34, 10
	s_sub_i32 s0, s16, s0
	s_cmp_lt_i32 s0, 0
	s_cselect_b32 s2, 41, 40
	s_mul_i32 s0, s2, s0
	s_add_i32 s0, s0, s1
	s_ashr_i32 s1, s0, 31
	s_lshr_b32 s1, s1, 28
	s_add_i32 s1, s0, s1
	s_ashr_i32 s2, s1, 4
	s_and_b32 s1, s1, 0xfff0
	s_sub_i32 s0, s0, s1
	s_bfe_i32 s1, s0, 0x80000
	s_bfe_u32 s1, s1, 0x2000d
	s_add_i32 s1, s0, s1
	s_bfe_i32 s3, s1, 0x80000
	s_and_b32 s1, s1, 0xfc
	s_sub_i32 s0, s0, s1
	s_lshl_b32 s2, s2, 2
	s_sext_i32_i16 s3, s3
	s_sext_i32_i8 s0, s0
	s_lshr_b32 s40, s3, 2
	s_add_i32 s0, s2, s0
	v_sub_u32_e32 v5, v5, v6
	s_ashr_i32 s1, s0, 31
	s_bfe_i64 s[2:3], s[40:41], 0x100000
	v_ashrrev_i16_sdwa v5, v230, sext(v5) dst_sel:DWORD dst_unused:UNUSED_PAD src0_sel:DWORD src1_sel:BYTE_0
	v_lshrrev_b32_e32 v6, 2, v3
	v_lshlrev_b32_e32 v7, 1, v3
	s_lshl_b64 s[26:27], s[0:1], 19
	s_lshl_b64 s[2:3], s[2:3], 19
	v_and_b32_e32 v4, 32, v4
	v_bfe_i32 v5, v5, 0, 16
	v_and_b32_e32 v6, 4, v6
	v_and_b32_e32 v7, 24, v7
	s_add_u32 s2, s22, s2
	v_or3_b32 v2, v2, v6, v7
	v_add_lshl_u32 v4, v4, v5, 1
	s_addc_u32 s3, s23, s3
	s_add_i32 s67, s25, 0
	v_lshl_add_u32 v194, v2, 11, v4
	s_mov_b64 s[30:31], s[2:3]
	s_add_i32 m0, s67, 0x10000
	v_lshl_add_u32 v196, v3, 11, v4
	global_load_lds_dwordx4 v194, s[30:31]
	s_add_i32 m0, s67, 0x12000
	s_add_u32 s50, s2, 0x40000
	s_addc_u32 s51, s3, 0
	global_load_lds_dwordx4 v170, s[30:31]
	s_mov_b64 s[30:31], s[50:51]
	s_add_i32 m0, s67, 0x14000
	s_nop 0
	global_load_lds_dwordx4 v194, s[30:31]
	s_add_i32 m0, s67, 0x16000
	s_add_u32 s26, s17, s26
	s_addc_u32 s27, s21, s27
	s_cmp_lg_u32 s100, 2
	s_cbranch_scc1 .Lh8_sx
	s_add_u32 s26, s26, 0x40000
	s_addc_u32 s27, s27, 0
.Lh8_sx:
	global_load_lds_dwordx4 v170, s[30:31]
	s_mov_b64 s[30:31], s[26:27]
	s_mov_b32 m0, s67
	s_add_i32 s68, s67, 0x2000
	s_nop 0
	global_load_lds_dwordx4 v196, s[30:31]
	s_mov_b32 m0, s68
	s_nop 0
	global_load_lds_dwordx4 v172, s[30:31]
	s_add_u32 s30, s26, 0x40000
	s_addc_u32 s31, s27, 0
	s_add_i32 s69, s67, 0x4000
	s_mov_b32 m0, s69
	s_add_i32 s70, s67, 0x6000
	s_cmp_eq_u32 s35, 1
	global_load_lds_dwordx4 v196, s[30:31]
	s_mov_b32 m0, s70
	s_cselect_b64 s[48:49], -1, 0
	global_load_lds_dwordx4 v172, s[30:31]
	s_cmp_lg_u32 s35, 1
	s_cbranch_scc1 .LBB0_1308
	s_barrier
.LBB0_1308:
	v_readlane_b32 s30, v255, 31
	v_readlane_b32 s31, v255, 32
	s_mov_b32 s57, s31
	s_mul_i32 s56, s8, 0xd800
	s_lshl_b64 s[30:31], s[56:57], 2
	s_add_u32 s1, s46, s30
	s_addc_u32 s55, s47, s31
	s_add_u32 s71, s46, 0x5e00000
	s_addc_u32 s72, s47, 0
	s_add_u32 s73, s1, 0x2000
	s_mov_b32 s31, s57
	s_addc_u32 s78, s55, 0
	s_lshl_b32 s56, s8, 10
	v_writelane_b32 v255, s30, 31
	v_mov_b32_e32 v195, v1
	s_waitcnt vmcnt(2)
	s_barrier
	v_writelane_b32 v255, s31, 32
	s_lshl_b64 s[30:31], s[56:57], 2
	s_waitcnt lgkmcnt(0)
	s_add_u32 s30, s18, s30
	s_addc_u32 s31, s19, s31
	s_add_u32 s79, s1, 0x4000
	s_addc_u32 s80, s55, 0
	s_ashr_i32 s1, s54, 31
	s_lshr_b32 s1, s1, 26
	s_add_i32 s1, s54, s1
	s_lshl_b32 s18, s34, 12
	s_ashr_i32 s84, s1, 6
	s_lshl_b32 s1, s35, 13
	s_and_b32 s55, s18, 0x3000
	s_add_u32 s34, s46, 0x6000000
	s_addc_u32 s35, s47, 0
	s_add_u32 s18, s2, 0x80
	s_addc_u32 s19, s3, 0
	s_add_i32 m0, s67, 0x18000
	v_lshl_add_u64 v[2:3], s[18:19], 0, v[194:195]
	v_mov_b32_e32 v171, v1
	global_load_lds_dwordx4 v[2:3], off
	s_add_i32 m0, s67, 0x1a000
	v_lshl_add_u64 v[2:3], s[18:19], 0, v[170:171]
	s_add_u32 s18, s26, 0x80
	v_mov_b32_e32 v197, v1
	s_addc_u32 s19, s27, 0
	s_add_i32 s82, s67, 0x8000
	v_mov_b32_e32 v173, v1
	global_load_lds_dwordx4 v[2:3], off
	s_mov_b32 m0, s82
	v_lshl_add_u64 v[2:3], s[18:19], 0, v[196:197]
	s_add_i32 s83, s67, 0xa000
	global_load_lds_dwordx4 v[2:3], off
	v_lshl_add_u64 v[2:3], s[18:19], 0, v[172:173]
	s_add_u32 s18, s50, 0x80
	s_mov_b32 m0, s83
	s_addc_u32 s19, s51, 0
	global_load_lds_dwordx4 v[2:3], off
	s_add_i32 m0, s67, 0x1c000
	v_lshl_add_u64 v[2:3], s[18:19], 0, v[194:195]
	global_load_lds_dwordx4 v[2:3], off
	v_lshl_add_u64 v[2:3], s[18:19], 0, v[170:171]
	s_add_i32 m0, s67, 0x1e000
	s_cmp_gt_i32 s54, 63
	global_load_lds_dwordx4 v[2:3], off
	v_and_b32_e32 v2, 15, v0
	v_and_b32_e32 v3, 48, v0
	v_lshlrev_b32_e32 v2, 6, v2
	v_lshlrev_b32_e32 v0, 2, v0
	s_cselect_b64 s[46:47], -1, 0
	s_add_i32 s81, s84, -2
	v_or_b32_e32 v4, v2, v3
	v_and_b32_e32 v0, 32, v0
	s_waitcnt vmcnt(6)
	s_cmpk_lt_u32 s41, 0x100
	v_bitop3_b32 v2, v2, v0, v3 bitop3:0x36
	v_bitop3_b32 v0, v4, s1, v0 bitop3:0xde
	s_cselect_b64 s[50:51], -1, 0
	s_add_u32 s85, s36, 0xff000000
	s_sext_i32_i8 s88, s40
	v_or_b32_e32 v222, s55, v2
	s_addc_u32 s86, s37, -1
	s_mov_b32 s87, 0
	s_mov_b32 s101, 0
	v_add_u32_e32 v223, 0, v0
	s_barrier
	s_branch .LBB0_1311
